# L0 LN1/LN2 row loops: all 8 row loads issued before the first wait (vmcnt(4) instead of vmcnt(0) between the halves)
# speedup vs baseline: 1.0043x; 1.0016x over previous
.LBB0_924:
	v_lshl_add_u64 v[18:19], s[72:73], 0, v[122:123]
	v_add_co_u32_e32 v14, vcc, 0x1ab00000, v18
	s_nop 1
	v_addc_co_u32_e32 v15, vcc, 0, v19, vcc
	global_load_dwordx4 v[6:9], v[14:15], off offset:1024
	global_load_dwordx4 v[2:5], v[14:15], off
	global_load_dwordx4 v[10:13], v[14:15], off offset:2048
	s_nop 0
	global_load_dwordx4 v[14:17], v[14:15], off offset:3072
	v_add_co_u32_e32 v30, vcc, 0x1ab01000, v18
	s_nop 1
	v_addc_co_u32_e32 v31, vcc, 0, v19, vcc
	global_load_dwordx4 v[18:21], v[30:31], off
	global_load_dwordx4 v[22:25], v[30:31], off offset:1024
	global_load_dwordx4 v[26:29], v[30:31], off offset:2048
	s_nop 0
	global_load_dwordx4 v[30:33], v[30:31], off offset:3072
	s_waitcnt vmcnt(4)
	v_mov_b32_e32 v36, v6
	v_mov_b32_e32 v37, v2
	v_mov_b32_e32 v38, v7
	v_mov_b32_e32 v39, v3
	v_mov_b32_e32 v40, v8
	v_mov_b32_e32 v41, v4
	v_mov_b32_e32 v42, v9
	v_mov_b32_e32 v43, v5
	v_mov_b32_e32 v44, v11
	v_mov_b32_e32 v45, v12
	v_mov_b32_e32 v46, v10
	v_mov_b32_e32 v47, v13
	v_pk_add_f32 v[36:37], v[36:37], v[38:39]
	v_pk_add_f32 v[38:39], v[40:41], v[42:43]
	v_pk_add_f32 v[40:41], v[44:45], v[46:47]
	v_pk_add_f32 v[36:37], v[36:37], v[38:39]
	v_pk_add_f32 v[38:39], v[40:41], v[40:41] op_sel_hi:[0,1]
	v_add_f32_e32 v34, 0, v37
	v_add_f32_e32 v49, v14, v15
	v_add_f32_e32 v51, v16, v17
	v_add_f32_e32 v43, v36, v34
	s_waitcnt vmcnt(3)
	v_mov_b32_e32 v48, v18
	v_mov_b32_e32 v50, v19
	v_mov_b32_e32 v42, v21
	v_mov_b32_e32 v38, v20
	s_waitcnt vmcnt(2)
	v_mov_b32_e32 v44, v23
	v_mov_b32_e32 v45, v24
	v_mov_b32_e32 v46, v22
	v_mov_b32_e32 v47, v25
	v_pk_add_f32 v[40:41], v[48:49], v[50:51]
	v_pk_add_f32 v[36:37], v[38:39], v[42:43]
	v_pk_add_f32 v[44:45], v[44:45], v[46:47]
	v_pk_add_f32 v[36:37], v[40:41], v[36:37]
	v_pk_add_f32 v[44:45], v[44:45], v[44:45] op_sel_hi:[0,1]
	v_pk_add_f32 v[36:37], v[36:37], v[36:37] op_sel_hi:[0,1]
	s_waitcnt vmcnt(1)
	v_add_f32_e32 v53, v26, v27
	v_add_f32_e32 v55, v28, v29
	s_waitcnt vmcnt(0)
	v_mov_b32_e32 v52, v30
	v_mov_b32_e32 v54, v31
	v_mov_b32_e32 v44, v32
	v_mov_b32_e32 v36, v33
	v_pk_add_f32 v[46:47], v[52:53], v[54:55]
	v_pk_add_f32 v[36:37], v[44:45], v[36:37]
	s_nop 0
	v_pk_add_f32 v[36:37], v[46:47], v[36:37]
	s_nop 0
	v_add_f32_e32 v34, v36, v37
	ds_bpermute_b32 v36, v130, v34
	s_waitcnt lgkmcnt(0)
	v_add_f32_e32 v34, v34, v36
	ds_bpermute_b32 v36, v131, v34
	s_waitcnt lgkmcnt(0)
	v_add_f32_e32 v34, v34, v36
	ds_bpermute_b32 v36, v132, v34
	s_waitcnt lgkmcnt(0)
	v_add_f32_e32 v34, v34, v36
	ds_bpermute_b32 v36, v133, v34
	s_waitcnt lgkmcnt(0)
	v_add_f32_e32 v34, v34, v36
	ds_bpermute_b32 v36, v134, v34
	s_waitcnt lgkmcnt(0)
	v_add_f32_e32 v34, v34, v36
	ds_bpermute_b32 v36, v135, v34
	s_waitcnt lgkmcnt(0)
	v_add_f32_e32 v121, v34, v36
	v_fmamk_f32 v126, v121, 0xba000000, v5
	v_fmamk_f32 v128, v121, 0xba000000, v4
	v_fmamk_f32 v4, v121, 0xba000000, v3
	v_fmamk_f32 v127, v121, 0xba000000, v9
	v_fmamk_f32 v5, v121, 0xba000000, v7
	v_fmac_f32_e32 v6, 0xba000000, v121
	v_fmamk_f32 v13, v121, 0xba000000, v13
	v_fmamk_f32 v12, v121, 0xba000000, v12
	v_fmamk_f32 v11, v121, 0xba000000, v11
	v_fmac_f32_e32 v10, 0xba000000, v121
	v_fmac_f32_e32 v2, 0xba000000, v121
	v_fmamk_f32 v129, v121, 0xba000000, v8
	v_mov_b32_e32 v3, v6
	v_pk_mul_f32 v[8:9], v[4:5], v[4:5]
	v_pk_mul_f32 v[36:37], v[126:127], v[126:127]
	v_pk_mul_f32 v[38:39], v[12:13], v[12:13]
	v_pk_mul_f32 v[40:41], v[10:11], v[10:11]
	v_fmamk_f32 v16, v121, 0xba000000, v16
	v_fmac_f32_e32 v14, 0xba000000, v121
	v_pk_fma_f32 v[8:9], v[2:3], v[2:3], v[8:9]
	v_pk_fma_f32 v[36:37], v[128:129], v[128:129], v[36:37]
	v_pk_mov_b32 v[52:53], v[40:41], v[38:39] op_sel:[1,0]
	v_mov_b32_e32 v41, v39
	v_fmamk_f32 v17, v121, 0xba000000, v17
	v_fmamk_f32 v15, v121, 0xba000000, v15
	v_fmamk_f32 v25, v121, 0xba000000, v25
	v_fmamk_f32 v24, v121, 0xba000000, v24
	v_fmamk_f32 v23, v121, 0xba000000, v23
	v_fmac_f32_e32 v22, 0xba000000, v121
	v_mul_f32_e32 v34, v14, v14
	v_mul_f32_e32 v42, v16, v16
	v_pk_add_f32 v[8:9], v[8:9], v[36:37]
	v_pk_add_f32 v[36:37], v[52:53], v[40:41]
	v_fmamk_f32 v21, v121, 0xba000000, v21
	v_fmamk_f32 v20, v121, 0xba000000, v20
	v_fmamk_f32 v19, v121, 0xba000000, v19
	v_fmac_f32_e32 v18, 0xba000000, v121
	v_pk_mul_f32 v[44:45], v[24:25], v[24:25]
	v_pk_mul_f32 v[46:47], v[22:23], v[22:23]
	v_pk_fma_f32 v[38:39], v[14:15], v[14:15], v[34:35] op_sel_hi:[1,1,0]
	v_pk_fma_f32 v[42:43], v[16:17], v[16:17], v[42:43] op_sel_hi:[1,1,0]
	v_pk_add_f32 v[8:9], v[8:9], v[8:9] op_sel_hi:[0,1]
	v_pk_add_f32 v[36:37], v[36:37], v[36:37] op_sel_hi:[0,1]
	v_fmamk_f32 v28, v121, 0xba000000, v28
	v_fmac_f32_e32 v26, 0xba000000, v121
	v_pk_mov_b32 v[54:55], v[46:47], v[44:45] op_sel:[1,0]
	v_mov_b32_e32 v47, v45
	v_mul_f32_e32 v38, v18, v18
	v_mul_f32_e32 v42, v19, v19
	v_mul_f32_e32 v36, v20, v20
	v_mul_f32_e32 v8, v21, v21
	v_fmamk_f32 v29, v121, 0xba000000, v29
	v_fmamk_f32 v27, v121, 0xba000000, v27
	v_mul_f32_e32 v48, v26, v26
	v_mul_f32_e32 v50, v28, v28
	v_pk_add_f32 v[40:41], v[54:55], v[46:47]
	v_pk_add_f32 v[38:39], v[38:39], v[42:43]
	v_pk_add_f32 v[8:9], v[36:37], v[8:9]
	v_pk_fma_f32 v[138:139], v[26:27], v[26:27], v[48:49] op_sel_hi:[1,1,0]
	v_pk_fma_f32 v[140:141], v[28:29], v[28:29], v[50:51] op_sel_hi:[1,1,0]
	v_pk_add_f32 v[142:143], v[40:41], v[40:41] op_sel_hi:[0,1]
	v_pk_add_f32 v[8:9], v[38:39], v[8:9]
	global_load_dwordx4 v[92:95], v[100:101], off
	global_load_dwordx4 v[84:87], v[100:101], off offset:1024
	global_load_dwordx4 v[96:99], v[102:103], off
	global_load_dwordx4 v[88:91], v[102:103], off offset:1024
	global_load_dwordx4 v[76:79], v[100:101], off offset:2048
	global_load_dwordx4 v[68:71], v[100:101], off offset:3072
	global_load_dwordx4 v[80:83], v[102:103], off offset:2048
	global_load_dwordx4 v[72:75], v[102:103], off offset:3072
	global_load_dwordx4 v[60:63], v[104:105], off
	global_load_dwordx4 v[64:67], v[106:107], off
	global_load_dwordx4 v[52:55], v[108:109], off
	global_load_dwordx4 v[56:59], v[110:111], off
	global_load_dwordx4 v[44:47], v[112:113], off
	global_load_dwordx4 v[48:51], v[114:115], off
	global_load_dwordx4 v[36:39], v[116:117], off
	global_load_dwordx4 v[40:43], v[118:119], off
	v_fmamk_f32 v33, v121, 0xba000000, v33
	v_pk_add_f32 v[8:9], v[8:9], v[8:9] op_sel_hi:[0,1]
	v_fmamk_f32 v32, v121, 0xba000000, v32
	v_fmamk_f32 v31, v121, 0xba000000, v31
	v_fmac_f32_e32 v30, 0xba000000, v121
	v_mul_f32_e32 v138, v30, v30
	v_mul_f32_e32 v140, v31, v31
	v_mul_f32_e32 v142, v32, v32
	v_mul_f32_e32 v8, v33, v33
	v_pk_add_f32 v[138:139], v[138:139], v[140:141]
	v_pk_add_f32 v[8:9], v[142:143], v[8:9]
	s_nop 0
	v_pk_add_f32 v[8:9], v[138:139], v[8:9]
	s_nop 0
	v_add_f32_e32 v3, v8, v9
	ds_bpermute_b32 v7, v130, v3
	s_waitcnt lgkmcnt(0)
	v_add_f32_e32 v3, v3, v7
	ds_bpermute_b32 v7, v131, v3
	s_waitcnt lgkmcnt(0)
	v_add_f32_e32 v3, v3, v7
	ds_bpermute_b32 v7, v132, v3
	s_waitcnt lgkmcnt(0)
	v_add_f32_e32 v3, v3, v7
	ds_bpermute_b32 v7, v133, v3
	s_waitcnt lgkmcnt(0)
	v_add_f32_e32 v3, v3, v7
	ds_bpermute_b32 v7, v134, v3
	s_waitcnt lgkmcnt(0)
	v_add_f32_e32 v3, v3, v7
	ds_bpermute_b32 v7, v135, v3
	s_waitcnt lgkmcnt(0)
	v_add_f32_e32 v3, v3, v7
	v_fmamk_f32 v3, v3, 0x3a000000, v136
	v_mul_f32_e32 v7, 0x4f800000, v3
	v_cmp_gt_f32_e32 vcc, s1, v3
	s_nop 1
	v_cndmask_b32_e32 v3, v3, v7, vcc
	v_sqrt_f32_e32 v7, v3
	s_nop 0
	v_add_u32_e32 v8, -1, v7
	v_add_u32_e32 v9, 1, v7
	v_fma_f32 v34, -v8, v7, v3
	v_fma_f32 v138, -v9, v7, v3
	v_cmp_ge_f32_e64 s[8:9], 0, v34
	s_nop 1
	v_cndmask_b32_e64 v7, v7, v8, s[8:9]
	v_cmp_lt_f32_e64 s[8:9], 0, v138
	s_nop 1
	v_cndmask_b32_e64 v7, v7, v9, s[8:9]
	v_mul_f32_e32 v8, 0x37800000, v7
	v_cndmask_b32_e32 v7, v7, v8, vcc
	v_cmp_class_f32_e32 vcc, v3, v137
	s_nop 1
	v_cndmask_b32_e32 v3, v7, v3, vcc
	v_div_scale_f32 v7, s[4:5], v3, v3, 1.0
	v_rcp_f32_e32 v8, v7
	s_nop 0
	v_fma_f32 v9, -v7, v8, 1.0
	v_fmac_f32_e32 v8, v9, v8
	v_div_scale_f32 v9, vcc, 1.0, v3, 1.0
	v_mul_f32_e32 v34, v9, v8
	v_fma_f32 v138, -v7, v34, v9
	v_fmac_f32_e32 v34, v138, v8
	v_fma_f32 v7, -v7, v34, v9
	v_div_fmas_f32 v7, v7, v8, v34
	v_div_fixup_f32 v34, v7, v3, 1.0
	s_and_saveexec_b64 s[4:5], s[6:7]
	s_cbranch_execz .LBB0_923
	v_mul_f32_e32 v8, 0x3a000000, v121
	v_ashrrev_i32_e32 v121, 31, v120
	v_lshl_add_u64 v[138:139], v[120:121], 2, s[14:15]
	v_mov_b32_e32 v9, v34
	global_store_dwordx2 v[138:139], v[8:9], off
	s_branch .LBB0_923

.LBB0_1139:
	v_lshl_add_u64 v[2:3], s[72:73], 0, v[120:121]
	v_add_co_u32_e32 v4, vcc, 0x1ab00000, v2
	s_nop 1
	v_addc_co_u32_e32 v5, vcc, 0, v3, vcc
	global_load_dwordx4 v[30:33], v[4:5], off
	global_load_dwordx4 v[26:29], v[4:5], off offset:1024
	global_load_dwordx4 v[22:25], v[4:5], off offset:2048
	global_load_dwordx4 v[18:21], v[4:5], off offset:3072
	v_add_co_u32_e32 v2, vcc, 0x1ab01000, v2
	s_nop 1
	v_addc_co_u32_e32 v3, vcc, 0, v3, vcc
	global_load_dwordx4 v[14:17], v[2:3], off
	global_load_dwordx4 v[10:13], v[2:3], off offset:1024
	global_load_dwordx4 v[6:9], v[2:3], off offset:2048
	s_nop 0
	global_load_dwordx4 v[2:5], v[2:3], off offset:3072
	s_waitcnt vmcnt(4)
	v_mov_b32_e32 v34, v30
	v_mov_b32_e32 v35, v26
	v_mov_b32_e32 v36, v31
	v_mov_b32_e32 v37, v27
	v_mov_b32_e32 v38, v32
	v_mov_b32_e32 v39, v28
	v_mov_b32_e32 v40, v33
	v_mov_b32_e32 v41, v29
	v_mov_b32_e32 v42, v23
	v_mov_b32_e32 v43, v24
	v_mov_b32_e32 v44, v22
	v_mov_b32_e32 v45, v25
	v_pk_add_f32 v[34:35], v[34:35], v[36:37]
	v_pk_add_f32 v[36:37], v[38:39], v[40:41]
	v_pk_add_f32 v[38:39], v[42:43], v[44:45]
	v_pk_add_f32 v[34:35], v[34:35], v[36:37]
	v_pk_add_f32 v[36:37], v[38:39], v[38:39] op_sel:[0,1] op_sel_hi:[1,0]
	v_add_f32_e32 v34, 0, v34
	v_add_f32_e32 v46, v18, v19
	v_add_f32_e32 v48, v20, v21
	v_add_f32_e32 v40, v34, v35
	s_waitcnt vmcnt(3)
	v_mov_b32_e32 v41, v14
	v_mov_b32_e32 v47, v16
	v_mov_b32_e32 v49, v17
	v_mov_b32_e32 v37, v15
	s_waitcnt vmcnt(2)
	v_mov_b32_e32 v42, v11
	v_mov_b32_e32 v43, v12
	v_mov_b32_e32 v44, v10
	v_mov_b32_e32 v45, v13
	v_pk_add_f32 v[38:39], v[46:47], v[48:49]
	v_pk_add_f32 v[34:35], v[40:41], v[36:37]
	v_pk_add_f32 v[42:43], v[42:43], v[44:45]
	v_pk_add_f32 v[34:35], v[34:35], v[38:39]
	v_pk_add_f32 v[42:43], v[42:43], v[42:43] op_sel:[0,1] op_sel_hi:[1,0]
	v_pk_add_f32 v[34:35], v[34:35], v[34:35] op_sel:[0,1] op_sel_hi:[1,0]
	s_waitcnt vmcnt(1)
	v_add_f32_e32 v50, v6, v7
	v_add_f32_e32 v52, v8, v9
	s_waitcnt vmcnt(0)
	v_mov_b32_e32 v51, v4
	v_mov_b32_e32 v53, v5
	v_mov_b32_e32 v43, v3
	v_mov_b32_e32 v35, v2
	v_pk_add_f32 v[44:45], v[50:51], v[52:53]
	v_pk_add_f32 v[34:35], v[34:35], v[42:43]
	s_nop 0
	v_pk_add_f32 v[34:35], v[34:35], v[44:45]
	s_nop 0
	v_add_f32_e32 v34, v34, v35
	ds_bpermute_b32 v35, v1, v34
	s_waitcnt lgkmcnt(0)
	v_add_f32_e32 v34, v34, v35
	ds_bpermute_b32 v35, v130, v34
	s_waitcnt lgkmcnt(0)
	v_add_f32_e32 v34, v34, v35
	ds_bpermute_b32 v35, v131, v34
	s_waitcnt lgkmcnt(0)
	v_add_f32_e32 v34, v34, v35
	ds_bpermute_b32 v35, v132, v34
	s_waitcnt lgkmcnt(0)
	v_add_f32_e32 v34, v34, v35
	ds_bpermute_b32 v35, v133, v34
	s_waitcnt lgkmcnt(0)
	v_add_f32_e32 v34, v34, v35
	ds_bpermute_b32 v35, v134, v34
	s_waitcnt lgkmcnt(0)
	v_add_f32_e32 v119, v34, v35
	v_fmamk_f32 v124, v119, 0xba000000, v33
	v_fmamk_f32 v128, v119, 0xba000000, v31
	v_fmamk_f32 v125, v119, 0xba000000, v29
	v_fmamk_f32 v129, v119, 0xba000000, v27
	v_fmac_f32_e32 v26, 0xba000000, v119
	v_fmamk_f32 v25, v119, 0xba000000, v25
	v_fmamk_f32 v24, v119, 0xba000000, v24
	v_fmamk_f32 v23, v119, 0xba000000, v23
	v_fmac_f32_e32 v22, 0xba000000, v119
	v_fmamk_f32 v126, v119, 0xba000000, v32
	v_fmac_f32_e32 v30, 0xba000000, v119
	v_fmamk_f32 v127, v119, 0xba000000, v28
	v_mov_b32_e32 v31, v26
	v_pk_mul_f32 v[28:29], v[128:129], v[128:129]
	v_pk_mul_f32 v[32:33], v[124:125], v[124:125]
	v_pk_mul_f32 v[34:35], v[24:25], v[24:25]
	v_pk_mul_f32 v[36:37], v[22:23], v[22:23]
	v_fmamk_f32 v20, v119, 0xba000000, v20
	v_fmac_f32_e32 v18, 0xba000000, v119
	v_pk_fma_f32 v[28:29], v[30:31], v[30:31], v[28:29]
	v_pk_fma_f32 v[32:33], v[126:127], v[126:127], v[32:33]
	v_pk_mov_b32 v[50:51], v[36:37], v[34:35] op_sel:[1,0]
	v_mov_b32_e32 v37, v35
	v_fmamk_f32 v21, v119, 0xba000000, v21
	v_fmamk_f32 v19, v119, 0xba000000, v19
	v_fmamk_f32 v13, v119, 0xba000000, v13
	v_fmamk_f32 v12, v119, 0xba000000, v12
	v_fmamk_f32 v11, v119, 0xba000000, v11
	v_fmac_f32_e32 v10, 0xba000000, v119
	v_mul_f32_e32 v38, v18, v18
	v_mul_f32_e32 v40, v20, v20
	v_pk_add_f32 v[28:29], v[28:29], v[32:33]
	v_pk_add_f32 v[32:33], v[50:51], v[36:37]
	v_fmamk_f32 v17, v119, 0xba000000, v17
	v_fmamk_f32 v16, v119, 0xba000000, v16
	v_fmamk_f32 v15, v119, 0xba000000, v15
	v_fmac_f32_e32 v14, 0xba000000, v119
	v_pk_mul_f32 v[42:43], v[12:13], v[12:13]
	v_pk_mul_f32 v[44:45], v[10:11], v[10:11]
	v_pk_fma_f32 v[34:35], v[18:19], v[18:19], v[38:39] op_sel_hi:[1,1,0]
	v_pk_fma_f32 v[38:39], v[20:21], v[20:21], v[40:41] op_sel_hi:[1,1,0]
	v_pk_add_f32 v[28:29], v[28:29], v[28:29] op_sel_hi:[0,1]
	v_pk_add_f32 v[32:33], v[32:33], v[32:33] op_sel_hi:[0,1]
	v_fmamk_f32 v8, v119, 0xba000000, v8
	v_fmac_f32_e32 v6, 0xba000000, v119
	v_pk_mov_b32 v[40:41], v[44:45], v[42:43] op_sel:[1,0]
	v_mov_b32_e32 v45, v43
	v_mul_f32_e32 v34, v14, v14
	v_mul_f32_e32 v38, v15, v15
	v_mul_f32_e32 v32, v16, v16
	v_mul_f32_e32 v28, v17, v17
	v_fmamk_f32 v9, v119, 0xba000000, v9
	v_fmamk_f32 v7, v119, 0xba000000, v7
	v_mul_f32_e32 v46, v6, v6
	v_mul_f32_e32 v48, v8, v8
	v_pk_add_f32 v[36:37], v[40:41], v[44:45]
	v_pk_add_f32 v[34:35], v[34:35], v[38:39]
	v_pk_add_f32 v[28:29], v[32:33], v[28:29]
	v_pk_fma_f32 v[136:137], v[6:7], v[6:7], v[46:47] op_sel_hi:[1,1,0]
	v_pk_fma_f32 v[138:139], v[8:9], v[8:9], v[48:49] op_sel_hi:[1,1,0]
	v_pk_add_f32 v[140:141], v[36:37], v[36:37] op_sel_hi:[0,1]
	v_pk_add_f32 v[28:29], v[34:35], v[28:29]
	global_load_dwordx4 v[88:91], v[98:99], off
	global_load_dwordx4 v[80:83], v[98:99], off offset:1024
	global_load_dwordx4 v[92:95], v[100:101], off
	global_load_dwordx4 v[84:87], v[100:101], off offset:1024
	global_load_dwordx4 v[72:75], v[98:99], off offset:2048
	global_load_dwordx4 v[64:67], v[98:99], off offset:3072
	global_load_dwordx4 v[76:79], v[100:101], off offset:2048
	global_load_dwordx4 v[68:71], v[100:101], off offset:3072
	global_load_dwordx4 v[56:59], v[102:103], off
	global_load_dwordx4 v[60:63], v[104:105], off
	global_load_dwordx4 v[48:51], v[106:107], off
	global_load_dwordx4 v[52:55], v[108:109], off
	global_load_dwordx4 v[40:43], v[110:111], off
	global_load_dwordx4 v[44:47], v[112:113], off
	global_load_dwordx4 v[32:35], v[114:115], off
	global_load_dwordx4 v[36:39], v[116:117], off
	v_fmamk_f32 v5, v119, 0xba000000, v5
	v_pk_add_f32 v[28:29], v[28:29], v[28:29] op_sel_hi:[0,1]
	v_fmamk_f32 v4, v119, 0xba000000, v4
	v_fmamk_f32 v3, v119, 0xba000000, v3
	v_fmac_f32_e32 v2, 0xba000000, v119
	v_mul_f32_e32 v136, v2, v2
	v_mul_f32_e32 v138, v3, v3
	v_mul_f32_e32 v140, v4, v4
	v_mul_f32_e32 v28, v5, v5
	v_pk_add_f32 v[136:137], v[136:137], v[138:139]
	v_pk_add_f32 v[28:29], v[140:141], v[28:29]
	s_nop 0
	v_pk_add_f32 v[28:29], v[136:137], v[28:29]
	s_nop 0
	v_add_f32_e32 v27, v28, v29
	ds_bpermute_b32 v28, v1, v27
	s_waitcnt lgkmcnt(0)
	v_add_f32_e32 v27, v27, v28
	ds_bpermute_b32 v28, v130, v27
	s_waitcnt lgkmcnt(0)
	v_add_f32_e32 v27, v27, v28
	ds_bpermute_b32 v28, v131, v27
	s_waitcnt lgkmcnt(0)
	v_add_f32_e32 v27, v27, v28
	ds_bpermute_b32 v28, v132, v27
	s_waitcnt lgkmcnt(0)
	v_add_f32_e32 v27, v27, v28
	ds_bpermute_b32 v28, v133, v27
	s_waitcnt lgkmcnt(0)
	v_add_f32_e32 v27, v27, v28
	ds_bpermute_b32 v28, v134, v27
	s_waitcnt lgkmcnt(0)
	v_add_f32_e32 v27, v27, v28
	v_fmamk_f32 v27, v27, 0x3a000000, v97
	v_mul_f32_e32 v28, 0x4f800000, v27
	v_cmp_gt_f32_e32 vcc, s1, v27
	s_nop 1
	v_cndmask_b32_e32 v27, v27, v28, vcc
	v_sqrt_f32_e32 v28, v27
	s_nop 0
	v_add_u32_e32 v29, -1, v28
	v_add_u32_e32 v31, 1, v28
	v_fma_f32 v136, -v29, v28, v27
	v_fma_f32 v137, -v31, v28, v27
	v_cmp_ge_f32_e64 s[8:9], 0, v136
	s_nop 1
	v_cndmask_b32_e64 v28, v28, v29, s[8:9]
	v_cmp_lt_f32_e64 s[8:9], 0, v137
	s_nop 1
	v_cndmask_b32_e64 v28, v28, v31, s[8:9]
	v_mul_f32_e32 v29, 0x37800000, v28
	v_cndmask_b32_e32 v28, v28, v29, vcc
	v_cmp_class_f32_e32 vcc, v27, v135
	s_nop 1
	v_cndmask_b32_e32 v27, v28, v27, vcc
	v_div_scale_f32 v28, s[4:5], v27, v27, 1.0
	v_rcp_f32_e32 v29, v28
	s_nop 0
	v_fma_f32 v31, -v28, v29, 1.0
	v_fmac_f32_e32 v29, v31, v29
	v_div_scale_f32 v31, vcc, 1.0, v27, 1.0
	v_mul_f32_e32 v136, v31, v29
	v_fma_f32 v137, -v28, v136, v31
	v_fmac_f32_e32 v136, v137, v29
	v_fma_f32 v28, -v28, v136, v31
	v_div_fmas_f32 v28, v28, v29, v136
	v_div_fixup_f32 v28, v28, v27, 1.0
	s_and_saveexec_b64 s[4:5], s[6:7]
	s_cbranch_execz .LBB0_1138
	v_mul_f32_e32 v136, 0x3a000000, v119
	v_ashrrev_i32_e32 v119, 31, v118
	v_lshl_add_u64 v[138:139], v[118:119], 2, s[16:17]
	v_mov_b32_e32 v137, v28
	global_store_dwordx2 v[138:139], v[136:137], off
	s_branch .LBB0_1138
